# baseline (speedup 1.0000x reference)
;     ...
;     float* ssl = (float*)(smem + 131072);
;     if (MODE == 0 || MODE == 3) {
;       char* ct = smem;
; #pragma unroll
;       for (int ai = 0; ai < 2; ++ai)
; #pragma unroll
;         for (int m = 0; m < 4; ++m) {
;           const int rloc = ai * HALF + wr * 64 + m * 16 + fr;
;           float rscale = 1.f;
;           if (MODE == 3) {
;             const long row = brow + rloc;
;             const float4 s0 = *(const float4*)(ssq + row * 8), s1 = *(const float4*)(ssq + row * 8 + 4);
;             rscale = rsqrtf((s0.x + s0.y + s0.z + s0.w + s1.x + s1.y + s1.z + s1.w) * (1.f / DM) + EPS);
;           }
; #pragma unroll
;           for (int bj = 0; bj < 2; ++bj)
; #pragma unroll
;             for (int n = 0; n < 2; ++n) {
;               const int cl = bj * HALF + wc * 32 + n * 16 + fq * 4;
;               f32x4 a = acc[ai][bj][m][n];
;               uint2 o;
;               o.x = pack2(a[0] * rscale, a[1] * rscale);
;               o.y = pack2(a[2] * rscale, a[3] * rscale);
;               *(uint2*)(ct + rloc * 528 + cl * 2) = o;
;             }
;         }
;       __syncthreads();
; #pragma unroll
;       for (int i = 0; i < 16; ++i) {
;         const int rloc = i * 16 + (tid_ >> 5), ch = tid_ & 31;
;         uint4 v = *(const uint4*)(ct + rloc * 528 + ch * 16);
;         typedef unsigned u32x4_t __attribute__((ext_vector_type(4)));
;         u32x4_t vv = {v.x, v.y, v.z, v.w};
;         __builtin_nontemporal_store(vv, (u32x4_t*)(Cb + (long)(brow + rloc) * ldc + bcol + ch * 8));
;       }
.LBB0_92:
	s_or_b64 exec, exec, s[0:1]
	s_cmpk_gt_i32 s31, 0xd7f
	s_barrier
	s_cbranch_scc1 .LBB0_101
	s_add_i32 s24, 0, 0x10000
	s_add_i32 s25, 0, 0x14000
	s_mov_b64 s[0:1], 0x80
	s_add_i32 s26, 0, 0x18000
	s_add_i32 s27, 0, 0x1c000
	s_mov_b64 s[2:3], 0x80080
	s_mov_b64 s[4:5], 0x100
	s_mov_b64 s[6:7], 0x80100
	s_mov_b64 s[8:9], 0x180
	s_mov_b64 s[10:11], 0x80180
	s_mov_b64 s[12:13], 0xf80
	s_movk_i32 s28, 0x210
	v_mov_b32_e32 v129, 0
	s_movk_i32 s29, 0x3600
	v_mov_b32_e32 v142, 1
	s_mov_b32 s30, s31
	s_mov_b32 s32, 0
	v_writelane_b32 v255, s34, 0
	v_writelane_b32 v255, s35, 1
	v_writelane_b32 v255, s36, 2
	v_writelane_b32 v255, s37, 3
	v_writelane_b32 v255, s38, 4
	v_writelane_b32 v255, s39, 5
	v_writelane_b32 v255, s40, 6
	v_writelane_b32 v255, s41, 7
	v_writelane_b32 v255, s42, 8
	v_writelane_b32 v255, s43, 9
	v_writelane_b32 v255, s44, 10
	v_writelane_b32 v255, s45, 11
	s_branch .LBB0_95
.LBB0_94:
	s_or_b64 exec, exec, s[18:19]
	s_mov_b32 s42, s16
	s_mov_b32 s43, s14
	s_add_i32 s30, s30, s33
	s_cmpk_lt_i32 s30, 0xd80
	s_cbranch_scc0 .Lp1_lasttile
	s_mov_b32 s32, 1
	s_branch .LBB0_95
.Lp1_lasttile:
	s_mov_b32 s32, 2
.Lp1_epi:
	v_and_b32_e32 v170, 15, v194
	v_bfe_u32 v171, v194, 4, 2
	v_bfe_u32 v172, v194, 6, 2
	v_mul_u32_u24_e32 v173, 0x210, v170
	v_lshlrev_b32_e32 v174, 6, v172
	v_lshl_add_u32 v174, v171, 3, v174
	v_add_u32_e32 v184, v173, v174
	v_add_u32_e32 v184, 0x18000, v184
	v_add_u32_e32 v185, 0x2100, v184
	v_add_u32_e32 v186, 0x4200, v184
	v_add_u32_e32 v187, 0x6300, v184
	v_lshrrev_b32_e32 v175, 5, v194
	v_and_b32_e32 v176, 31, v194
	v_mul_u32_u24_e32 v177, 0x210, v175
	v_lshl_add_u32 v177, v176, 4, v177
	v_add_u32_e32 v177, 0x18000, v177
	v_readfirstlane_b32 s34, v194
	s_lshl_b32 s36, s43, 1
	s_add_u32 s36, s76, s36
	s_addc_u32 s37, s77, 0
	s_lshr_b32 s34, s34, 8
	v_add_u32_e32 v178, s42, v175
	v_lshlrev_b32_e32 v180, 4, v176
	v_mov_b32_e32 v181, 0
	v_lshl_add_u64 v[180:181], s[36:37], 0, v[180:181]
	s_movk_i32 s38, 0x3600
	v_mad_u64_u32 v[182:183], s[40:41], v178, s38, v[180:181]
	s_mov_b32 s44, 0x36000
	s_mov_b32 s45, 0
	s_cmp_lg_u32 s34, 0
	s_cbranch_scc1 .Lp1_q0r
	v_cvt_pk_bf16_f32 v108, v108, v109
	v_cvt_pk_bf16_f32 v109, v110, v111
	v_cvt_pk_bf16_f32 v104, v104, v105
	v_cvt_pk_bf16_f32 v105, v106, v107
	ds_write2_b64 v184, v[108:109], v[104:105] offset1:4
	v_cvt_pk_bf16_f32 v124, v124, v125
	v_cvt_pk_bf16_f32 v125, v126, v127
	v_cvt_pk_bf16_f32 v120, v120, v121
	v_cvt_pk_bf16_f32 v121, v122, v123
	ds_write2_b64 v184, v[124:125], v[120:121] offset0:32 offset1:36
	v_cvt_pk_bf16_f32 v96, v96, v97
	v_cvt_pk_bf16_f32 v97, v98, v99
	v_cvt_pk_bf16_f32 v84, v84, v85
	v_cvt_pk_bf16_f32 v85, v86, v87
	ds_write2_b64 v185, v[96:97], v[84:85] offset1:4
	v_cvt_pk_bf16_f32 v116, v116, v117
	v_cvt_pk_bf16_f32 v117, v118, v119
	v_cvt_pk_bf16_f32 v112, v112, v113
	v_cvt_pk_bf16_f32 v113, v114, v115
	ds_write2_b64 v185, v[116:117], v[112:113] offset0:32 offset1:36
	v_cvt_pk_bf16_f32 v64, v64, v65
	v_cvt_pk_bf16_f32 v65, v66, v67
	v_cvt_pk_bf16_f32 v56, v56, v57
	v_cvt_pk_bf16_f32 v57, v58, v59
	ds_write2_b64 v186, v[64:65], v[56:57] offset1:4
	v_cvt_pk_bf16_f32 v100, v100, v101
	v_cvt_pk_bf16_f32 v101, v102, v103
	v_cvt_pk_bf16_f32 v88, v88, v89
	v_cvt_pk_bf16_f32 v89, v90, v91
	ds_write2_b64 v186, v[100:101], v[88:89] offset0:32 offset1:36
	v_cvt_pk_bf16_f32 v36, v36, v37
	v_cvt_pk_bf16_f32 v37, v38, v39
	v_cvt_pk_bf16_f32 v32, v32, v33
	v_cvt_pk_bf16_f32 v33, v34, v35
	ds_write2_b64 v187, v[36:37], v[32:33] offset1:4
	v_cvt_pk_bf16_f32 v68, v68, v69
	v_cvt_pk_bf16_f32 v69, v70, v71
	v_cvt_pk_bf16_f32 v60, v60, v61
	v_cvt_pk_bf16_f32 v61, v62, v63
	ds_write2_b64 v187, v[68:69], v[60:61] offset0:32 offset1:36
.Lp1_q0r:
	s_waitcnt lgkmcnt(0)
	s_barrier
	ds_read_b128 v[222:225], v177
	ds_read_b128 v[226:229], v177 offset:8448
	ds_read_b128 v[230:233], v177 offset:16896
	ds_read_b128 v[234:237], v177 offset:25344
	v_lshl_add_u64 v[238:239], v[182:183], 0, s[44:45]
	v_lshl_add_u64 v[240:241], v[238:239], 0, s[44:45]
	v_lshl_add_u64 v[242:243], v[240:241], 0, s[44:45]
	v_lshl_add_u64 v[244:245], v[242:243], 0, s[44:45]
	s_waitcnt lgkmcnt(3)
	global_store_dwordx4 v[182:183], v[222:225], off nt
	s_waitcnt lgkmcnt(2)
	global_store_dwordx4 v[238:239], v[226:229], off nt
	s_waitcnt lgkmcnt(1)
	global_store_dwordx4 v[240:241], v[230:233], off nt
	s_waitcnt lgkmcnt(0)
	global_store_dwordx4 v[242:243], v[234:237], off nt
	s_nop 1
	v_mov_b64_e32 v[182:183], v[244:245]
	s_barrier
	s_cmp_lg_u32 s34, 1
	s_cbranch_scc1 .Lp1_q1r
	v_cvt_pk_bf16_f32 v108, v108, v109
	v_cvt_pk_bf16_f32 v109, v110, v111
	v_cvt_pk_bf16_f32 v104, v104, v105
	v_cvt_pk_bf16_f32 v105, v106, v107
	ds_write2_b64 v184, v[108:109], v[104:105] offset1:4
	v_cvt_pk_bf16_f32 v124, v124, v125
	v_cvt_pk_bf16_f32 v125, v126, v127
	v_cvt_pk_bf16_f32 v120, v120, v121
	v_cvt_pk_bf16_f32 v121, v122, v123
	ds_write2_b64 v184, v[124:125], v[120:121] offset0:32 offset1:36
	v_cvt_pk_bf16_f32 v96, v96, v97
	v_cvt_pk_bf16_f32 v97, v98, v99
	v_cvt_pk_bf16_f32 v84, v84, v85
	v_cvt_pk_bf16_f32 v85, v86, v87
	ds_write2_b64 v185, v[96:97], v[84:85] offset1:4
	v_cvt_pk_bf16_f32 v116, v116, v117
	v_cvt_pk_bf16_f32 v117, v118, v119
	v_cvt_pk_bf16_f32 v112, v112, v113
	v_cvt_pk_bf16_f32 v113, v114, v115
	ds_write2_b64 v185, v[116:117], v[112:113] offset0:32 offset1:36
	v_cvt_pk_bf16_f32 v64, v64, v65
	v_cvt_pk_bf16_f32 v65, v66, v67
	v_cvt_pk_bf16_f32 v56, v56, v57
	v_cvt_pk_bf16_f32 v57, v58, v59
	ds_write2_b64 v186, v[64:65], v[56:57] offset1:4
	v_cvt_pk_bf16_f32 v100, v100, v101
	v_cvt_pk_bf16_f32 v101, v102, v103
	v_cvt_pk_bf16_f32 v88, v88, v89
	v_cvt_pk_bf16_f32 v89, v90, v91
	ds_write2_b64 v186, v[100:101], v[88:89] offset0:32 offset1:36
	v_cvt_pk_bf16_f32 v36, v36, v37
	v_cvt_pk_bf16_f32 v37, v38, v39
	v_cvt_pk_bf16_f32 v32, v32, v33
	v_cvt_pk_bf16_f32 v33, v34, v35
	ds_write2_b64 v187, v[36:37], v[32:33] offset1:4
	v_cvt_pk_bf16_f32 v68, v68, v69
	v_cvt_pk_bf16_f32 v69, v70, v71
	v_cvt_pk_bf16_f32 v60, v60, v61
	v_cvt_pk_bf16_f32 v61, v62, v63
	ds_write2_b64 v187, v[68:69], v[60:61] offset0:32 offset1:36
;     ...
;       for (int ai = 0; ai < 2; ++ai)
; #pragma unroll
;         for (int m = 0; m < 4; ++m) {
;           const int rloc = ai * HALF + wr * 64 + m * 16 + fr;
;           float rscale = 1.f;
;           if (MODE == 3) {
;             const long row = brow + rloc;
;             const float4 s0 = *(const float4*)(ssq + row * 8), s1 = *(const float4*)(ssq + row * 8 + 4);
;             rscale = rsqrtf((s0.x + s0.y + s0.z + s0.w + s1.x + s1.y + s1.z + s1.w) * (1.f / DM) + EPS);
;           }
; #pragma unroll
;           for (int bj = 0; bj < 2; ++bj)
; #pragma unroll
;             for (int n = 0; n < 2; ++n) {
;               const int cl = bj * HALF + wc * 32 + n * 16 + fq * 4;
;               f32x4 a = acc[ai][bj][m][n];
;               uint2 o;
;               o.x = pack2(a[0] * rscale, a[1] * rscale);
;               o.y = pack2(a[2] * rscale, a[3] * rscale);
;               *(uint2*)(ct + rloc * 528 + cl * 2) = o;
;             }
;         }
;       __syncthreads();
; #pragma unroll
;       for (int i = 0; i < 16; ++i) {
;         const int rloc = i * 16 + (tid_ >> 5), ch = tid_ & 31;
;         uint4 v = *(const uint4*)(ct + rloc * 528 + ch * 16);
;         typedef unsigned u32x4_t __attribute__((ext_vector_type(4)));
;         u32x4_t vv = {v.x, v.y, v.z, v.w};
;         __builtin_nontemporal_store(vv, (u32x4_t*)(Cb + (long)(brow + rloc) * ldc + bcol + ch * 8));
;       }
.Lp1_q1r:
	s_waitcnt lgkmcnt(0)
	s_barrier
	ds_read_b128 v[222:225], v177
	ds_read_b128 v[226:229], v177 offset:8448
	ds_read_b128 v[230:233], v177 offset:16896
	ds_read_b128 v[234:237], v177 offset:25344
	v_lshl_add_u64 v[238:239], v[182:183], 0, s[44:45]
	v_lshl_add_u64 v[240:241], v[238:239], 0, s[44:45]
	v_lshl_add_u64 v[242:243], v[240:241], 0, s[44:45]
	v_lshl_add_u64 v[244:245], v[242:243], 0, s[44:45]
	s_waitcnt lgkmcnt(3)
	global_store_dwordx4 v[182:183], v[222:225], off nt
	s_waitcnt lgkmcnt(2)
	global_store_dwordx4 v[238:239], v[226:229], off nt
	s_waitcnt lgkmcnt(1)
	global_store_dwordx4 v[240:241], v[230:233], off nt
	s_waitcnt lgkmcnt(0)
	global_store_dwordx4 v[242:243], v[234:237], off nt
	s_nop 1
	v_mov_b64_e32 v[182:183], v[244:245]
	s_barrier
	s_cmp_lg_u32 s34, 0
	s_cbranch_scc1 .Lp1_q2r
	v_cvt_pk_bf16_f32 v76, v76, v77
	v_cvt_pk_bf16_f32 v77, v78, v79
	v_cvt_pk_bf16_f32 v72, v72, v73
	v_cvt_pk_bf16_f32 v73, v74, v75
	ds_write2_b64 v184, v[76:77], v[72:73] offset1:4
	v_cvt_pk_bf16_f32 v92, v92, v93
	v_cvt_pk_bf16_f32 v93, v94, v95
	v_cvt_pk_bf16_f32 v80, v80, v81
	v_cvt_pk_bf16_f32 v81, v82, v83
	ds_write2_b64 v184, v[92:93], v[80:81] offset0:32 offset1:36
	v_cvt_pk_bf16_f32 v44, v44, v45
	v_cvt_pk_bf16_f32 v45, v46, v47
	v_cvt_pk_bf16_f32 v40, v40, v41
	v_cvt_pk_bf16_f32 v41, v42, v43
	ds_write2_b64 v185, v[44:45], v[40:41] offset1:4
	v_cvt_pk_bf16_f32 v52, v52, v53
	v_cvt_pk_bf16_f32 v53, v54, v55
	v_cvt_pk_bf16_f32 v48, v48, v49
	v_cvt_pk_bf16_f32 v49, v50, v51
	ds_write2_b64 v185, v[52:53], v[48:49] offset0:32 offset1:36
	v_cvt_pk_bf16_f32 v20, v20, v21
	v_cvt_pk_bf16_f32 v21, v22, v23
	v_cvt_pk_bf16_f32 v16, v16, v17
	v_cvt_pk_bf16_f32 v17, v18, v19
	ds_write2_b64 v186, v[20:21], v[16:17] offset1:4
	v_cvt_pk_bf16_f32 v28, v28, v29
	v_cvt_pk_bf16_f32 v29, v30, v31
	v_cvt_pk_bf16_f32 v24, v24, v25
	v_cvt_pk_bf16_f32 v25, v26, v27
	ds_write2_b64 v186, v[28:29], v[24:25] offset0:32 offset1:36
	v_cvt_pk_bf16_f32 v4, v4, v5
	v_cvt_pk_bf16_f32 v5, v6, v7
	v_cvt_pk_bf16_f32 v0, v0, v1
	v_cvt_pk_bf16_f32 v1, v2, v3
	ds_write2_b64 v187, v[4:5], v[0:1] offset1:4
	v_cvt_pk_bf16_f32 v12, v12, v13
	v_cvt_pk_bf16_f32 v13, v14, v15
	v_cvt_pk_bf16_f32 v8, v8, v9
	v_cvt_pk_bf16_f32 v9, v10, v11
	ds_write2_b64 v187, v[12:13], v[8:9] offset0:32 offset1:36
.Lp1_q2r:
	s_waitcnt lgkmcnt(0)
	s_barrier
	ds_read_b128 v[222:225], v177
	ds_read_b128 v[226:229], v177 offset:8448
	ds_read_b128 v[230:233], v177 offset:16896
	ds_read_b128 v[234:237], v177 offset:25344
	v_lshl_add_u64 v[238:239], v[182:183], 0, s[44:45]
	v_lshl_add_u64 v[240:241], v[238:239], 0, s[44:45]
	v_lshl_add_u64 v[242:243], v[240:241], 0, s[44:45]
	v_lshl_add_u64 v[244:245], v[242:243], 0, s[44:45]
	s_waitcnt lgkmcnt(3)
	global_store_dwordx4 v[182:183], v[222:225], off nt
	s_waitcnt lgkmcnt(2)
	global_store_dwordx4 v[238:239], v[226:229], off nt
	s_waitcnt lgkmcnt(1)
	global_store_dwordx4 v[240:241], v[230:233], off nt
	s_waitcnt lgkmcnt(0)
	global_store_dwordx4 v[242:243], v[234:237], off nt
	s_nop 1
	v_mov_b64_e32 v[182:183], v[244:245]
	s_barrier
	s_cmp_lg_u32 s34, 1
	s_cbranch_scc1 .Lp1_q3r
	v_cvt_pk_bf16_f32 v76, v76, v77
	v_cvt_pk_bf16_f32 v77, v78, v79
	v_cvt_pk_bf16_f32 v72, v72, v73
	v_cvt_pk_bf16_f32 v73, v74, v75
	ds_write2_b64 v184, v[76:77], v[72:73] offset1:4
	v_cvt_pk_bf16_f32 v92, v92, v93
	v_cvt_pk_bf16_f32 v93, v94, v95
	v_cvt_pk_bf16_f32 v80, v80, v81
	v_cvt_pk_bf16_f32 v81, v82, v83
	ds_write2_b64 v184, v[92:93], v[80:81] offset0:32 offset1:36
	v_cvt_pk_bf16_f32 v44, v44, v45
	v_cvt_pk_bf16_f32 v45, v46, v47
	v_cvt_pk_bf16_f32 v40, v40, v41
	v_cvt_pk_bf16_f32 v41, v42, v43
	ds_write2_b64 v185, v[44:45], v[40:41] offset1:4
	v_cvt_pk_bf16_f32 v52, v52, v53
	v_cvt_pk_bf16_f32 v53, v54, v55
	v_cvt_pk_bf16_f32 v48, v48, v49
	v_cvt_pk_bf16_f32 v49, v50, v51
	ds_write2_b64 v185, v[52:53], v[48:49] offset0:32 offset1:36
	v_cvt_pk_bf16_f32 v20, v20, v21
	v_cvt_pk_bf16_f32 v21, v22, v23
	v_cvt_pk_bf16_f32 v16, v16, v17
	v_cvt_pk_bf16_f32 v17, v18, v19
	ds_write2_b64 v186, v[20:21], v[16:17] offset1:4
	v_cvt_pk_bf16_f32 v28, v28, v29
	v_cvt_pk_bf16_f32 v29, v30, v31
	v_cvt_pk_bf16_f32 v24, v24, v25
	v_cvt_pk_bf16_f32 v25, v26, v27
	ds_write2_b64 v186, v[28:29], v[24:25] offset0:32 offset1:36
	v_cvt_pk_bf16_f32 v4, v4, v5
	v_cvt_pk_bf16_f32 v5, v6, v7
	v_cvt_pk_bf16_f32 v0, v0, v1
	v_cvt_pk_bf16_f32 v1, v2, v3
	ds_write2_b64 v187, v[4:5], v[0:1] offset1:4
	v_cvt_pk_bf16_f32 v12, v12, v13
	v_cvt_pk_bf16_f32 v13, v14, v15
	v_cvt_pk_bf16_f32 v8, v8, v9
	v_cvt_pk_bf16_f32 v9, v10, v11
	ds_write2_b64 v187, v[12:13], v[8:9] offset0:32 offset1:36
.Lp1_q3r:
	s_waitcnt lgkmcnt(0)
	s_barrier
	ds_read_b128 v[222:225], v177
	ds_read_b128 v[226:229], v177 offset:8448
	ds_read_b128 v[230:233], v177 offset:16896
	ds_read_b128 v[234:237], v177 offset:25344
	v_lshl_add_u64 v[238:239], v[182:183], 0, s[44:45]
	v_lshl_add_u64 v[240:241], v[238:239], 0, s[44:45]
	v_lshl_add_u64 v[242:243], v[240:241], 0, s[44:45]
	v_lshl_add_u64 v[244:245], v[242:243], 0, s[44:45]
	s_waitcnt lgkmcnt(3)
	global_store_dwordx4 v[182:183], v[222:225], off nt
	s_waitcnt lgkmcnt(2)
	global_store_dwordx4 v[238:239], v[226:229], off nt
	s_waitcnt lgkmcnt(1)
	global_store_dwordx4 v[240:241], v[230:233], off nt
	s_waitcnt lgkmcnt(0)
	global_store_dwordx4 v[242:243], v[234:237], off nt
	s_nop 1
	v_mov_b64_e32 v[182:183], v[244:245]
	s_barrier
	s_cmp_eq_u32 s32, 1
	s_cbranch_scc1 .Lp1_hdr2
	s_branch .Lp1_exit
;     ...
;   for (int vw = blockIdx.x; vw < nwg; vw += gridDim.x) {
;     int tid_ = threadIdx.x;
;     asm volatile("" : "+v"(tid_));
;     const int wid = tid_ >> 6, lane = tid_ & 63, wr = wid >> 2, wc = wid & 3, fr = lane & 15, fq = lane >> 4;
;     int brow, bcol;
;     TILE_COORDS(vw, brow, bcol);
;     f32x4 acc[2][2][4][2] = {};
;     bf16x8 At[4][2], B0[2][2], B1[2][2];
;     STAGE(SB(0, 0), Bt, bcol, 0); STAGE(SA(0, 0), A, brow, 0);
;     STAGE(SB(0, 1), Bt, bcol + HALF, 0); STAGE(SA(0, 1), A, brow + HALF, 0);
.LBB0_95:
	s_ashr_i32 s14, s30, 31
	s_lshr_b32 s14, s14, 29
	s_add_i32 s14, s30, s14
	s_ashr_i32 s15, s14, 3
	s_and_b32 s14, s14, -8
	s_sub_i32 s14, s30, s14
	s_cmp_lt_i32 s14, 0
	s_movk_i32 s16, 0x1b1
	s_cselect_b32 s16, s16, 0x1b0
	v_mov_b32_e32 v128, v194
	s_mul_i32 s14, s16, s14
	s_add_i32 s14, s14, s15
	v_ashrrev_i32_e32 v200, 31, v128
	s_mul_hi_i32 s15, s14, 0x4bda12f7
	v_lshrrev_b32_e32 v200, 26, v200
	s_lshr_b32 s16, s15, 31
	s_ashr_i32 s15, s15, 5
	v_add_u32_e32 v200, v128, v200
	s_add_i32 s20, s15, s16
	v_ashrrev_i32_e32 v201, 6, v200
	v_bfe_i32 v200, v128, 27, 1
	s_mul_i32 s15, s20, 0x6c
	v_lshlrev_b32_e32 v143, 4, v128
	v_lshrrev_b32_e32 v200, 22, v200
	s_sub_i32 s14, s14, s15
	v_add_u32_e32 v200, v143, v200
	s_bfe_i32 s15, s14, 0x80000
	v_and_b32_e32 v200, 0xfffffc00, v200
	s_bfe_u32 s15, s15, 0x2000d
	v_sub_u32_e32 v200, v143, v200
	s_add_i32 s15, s14, s15
	v_lshrrev_b32_e32 v202, 4, v200
	s_bfe_i32 s16, s15, 0x80000
	s_and_b32 s15, s15, 0xfc
	v_bitop3_b32 v202, v202, v200, 32 bitop3:0x6c
	s_sub_i32 s14, s14, s15
	v_ashrrev_i32_e32 v203, 31, v202
	s_sext_i32_i16 s16, s16
	s_sext_i32_i8 s14, s14
	v_lshrrev_b32_e32 v203, 26, v203
	s_lshl_b32 s21, s14, 8
	s_lshl_b32 s14, s16, 6
	v_add_u32_e32 v203, v202, v203
	s_and_b32 s14, s14, 0xffffff00
	v_lshlrev_b32_e32 v200, 3, v201
	v_ashrrev_i32_e32 v204, 6, v203
	v_and_b32_e32 v203, 0xc0, v203
	s_ashr_i32 s15, s14, 31
	v_and_b32_e32 v200, -16, v200
	v_lshlrev_b32_e32 v201, 5, v201
	v_sub_u32_e32 v202, v202, v203
	s_lshl_b64 s[18:19], s[14:15], 12
	v_add_u32_e32 v200, v204, v200
	v_and_b32_e32 v201, 32, v201
	v_ashrrev_i16_sdwa v202, v142, sext(v202) dst_sel:DWORD dst_unused:UNUSED_PAD src0_sel:DWORD src1_sel:BYTE_0
	s_add_u32 s16, s82, s18
	v_add_u32_sdwa v202, v201, sext(v202) dst_sel:DWORD dst_unused:UNUSED_PAD src0_sel:DWORD src1_sel:WORD_0
	v_ashrrev_i32_e32 v201, 31, v200
	s_addc_u32 s17, s83, s19
	v_lshlrev_b64 v[200:201], 12, v[200:201]
	v_ashrrev_i32_e32 v203, 31, v202
	v_lshl_add_u64 v[204:205], s[16:17], 0, v[200:201]
	v_lshlrev_b64 v[202:203], 1, v[202:203]
	v_add_u32_e32 v220, 0x2000, v143
	v_lshl_add_u64 v[208:209], v[204:205], 0, v[202:203]
	v_ashrrev_i32_e32 v204, 31, v220
	v_lshrrev_b32_e32 v204, 22, v204
	v_add_u32_e32 v204, v220, v204
	v_ashrrev_i32_e32 v205, 10, v204
	v_mul_i32_i24_e32 v204, 0x400, v205
	v_sub_u32_e32 v204, v220, v204
	v_lshrrev_b32_e32 v206, 4, v204
	v_bitop3_b32 v206, v206, v204, 32 bitop3:0x6c
	v_ashrrev_i32_e32 v207, 31, v206
	v_lshrrev_b32_e32 v207, 26, v207
	v_add_u32_e32 v207, v206, v207
	v_lshlrev_b32_e32 v204, 3, v205
	v_ashrrev_i32_e32 v210, 6, v207
	v_and_b32_e32 v207, 0xc0, v207
	v_and_b32_e32 v204, -16, v204
	v_lshlrev_b32_e32 v205, 5, v205
	v_sub_u32_e32 v206, v206, v207
	v_add_u32_e32 v204, v210, v204
	v_and_b32_e32 v205, 32, v205
	v_ashrrev_i16_sdwa v206, v142, sext(v206) dst_sel:DWORD dst_unused:UNUSED_PAD src0_sel:DWORD src1_sel:BYTE_0
	v_add_u32_e32 v147, s24, v143
	v_add_u32_sdwa v206, v205, sext(v206) dst_sel:DWORD dst_unused:UNUSED_PAD src0_sel:DWORD src1_sel:WORD_0
	v_ashrrev_i32_e32 v205, 31, v204
	v_readfirstlane_b32 s22, v147
	v_lshlrev_b64 v[204:205], 12, v[204:205]
	v_add_u32_e32 v212, s24, v220
	s_mov_b32 m0, s22
	v_lshl_add_u64 v[210:211], s[16:17], 0, v[204:205]
	v_readfirstlane_b32 s16, v212
	global_load_lds_dwordx4 v[208:209], off
	s_mov_b32 m0, s16
	s_lshl_b32 s16, s20, 10
	s_add_i32 s16, s21, s16
	s_ashr_i32 s17, s16, 31
	s_lshl_b64 s[20:21], s[16:17], 12
	s_add_u32 s22, s78, s20
	s_addc_u32 s23, s79, s21
	v_lshl_add_u64 v[212:213], s[22:23], 0, v[200:201]
	v_lshl_add_u64 v[214:215], s[22:23], 0, v[204:205]
	s_or_b32 s22, s14, 0x80
	s_ashr_i32 s23, s22, 31
	s_lshl_b64 s[22:23], s[22:23], 12
	s_add_u32 s22, s82, s22
	v_ashrrev_i32_e32 v207, 31, v206
	s_addc_u32 s23, s83, s23
	v_lshlrev_b64 v[206:207], 1, v[206:207]
	v_add_u32_e32 v153, 0, v143
	v_lshl_add_u64 v[216:217], s[22:23], 0, v[200:201]
	v_lshl_add_u64 v[218:219], s[22:23], 0, v[204:205]
	s_or_b32 s22, s16, 0x80
	v_lshl_add_u64 v[210:211], v[210:211], 0, v[206:207]
	v_readfirstlane_b32 s17, v153
	v_add_u32_e32 v154, 0x2000, v153
	s_ashr_i32 s23, s22, 31
	global_load_lds_dwordx4 v[210:211], off
	v_lshl_add_u64 v[212:213], v[212:213], 0, v[202:203]
	s_mov_b32 m0, s17
	v_readfirstlane_b32 s17, v154
	v_add_u32_e32 v155, s25, v143
	s_lshl_b64 s[22:23], s[22:23], 12
	global_load_lds_dwordx4 v[212:213], off
	v_lshl_add_u64 v[214:215], v[214:215], 0, v[206:207]
	s_mov_b32 m0, s17
	v_readfirstlane_b32 s17, v155
	v_add_u32_e32 v220, s25, v220
	s_add_u32 s22, s78, s22
	global_load_lds_dwordx4 v[214:215], off
	v_lshl_add_u64 v[216:217], v[216:217], 0, v[202:203]
	s_mov_b32 m0, s17
	v_readfirstlane_b32 s17, v220
	s_addc_u32 s23, s79, s23
	v_add_u32_e32 v157, 0x4000, v153
	global_load_lds_dwordx4 v[216:217], off
	v_lshl_add_u64 v[218:219], v[218:219], 0, v[206:207]
	s_mov_b32 m0, s17
	v_lshl_add_u64 v[220:221], s[22:23], 0, v[200:201]
	v_readfirstlane_b32 s17, v157
	v_add_u32_e32 v158, 0x6000, v153
	global_load_lds_dwordx4 v[218:219], off
	v_lshl_add_u64 v[130:131], v[220:221], 0, v[202:203]
	s_mov_b32 m0, s17
	v_lshl_add_u64 v[220:221], s[22:23], 0, v[204:205]
	v_readfirstlane_b32 s17, v158
	global_load_lds_dwordx4 v[130:131], off
	v_lshl_add_u64 v[132:133], v[220:221], 0, v[206:207]
	s_mov_b32 m0, s17
	v_ashrrev_i32_e32 v220, 8, v128
	global_load_lds_dwordx4 v[132:133], off
	s_cmp_lg_u32 s32, 0
	s_cbranch_scc1 .Lp1_epi
; #define WAIT_V(n) asm volatile("s_waitcnt vmcnt(" #n ")" ::: "memory")
; #define BAR __builtin_amdgcn_s_barrier()
;     ...
;     f32x4 acc[2][2][4][2] = {};
;     bf16x8 At[4][2], B0[2][2], B1[2][2];
;     STAGE(SB(0, 0), Bt, bcol, 0); STAGE(SA(0, 0), A, brow, 0);
;     STAGE(SB(0, 1), Bt, bcol + HALF, 0); STAGE(SA(0, 1), A, brow + HALF, 0);
;     if (wr == 1) BAR;
;     WAIT_V(4); BAR;
;     STAGE(SB(1, 0), Bt, bcol, 1); STAGE(SA(1, 0), A, brow, 1); STAGE(SB(1, 1), Bt, bcol + HALF, 1);
;     WAIT_V(6); BAR;
.Lp1_hdr2:
	v_mov_b64_e32 v[22:23], 0
	v_mov_b64_e32 v[24:25], 0
	v_mov_b64_e32 v[26:27], 0
	v_mov_b64_e32 v[28:29], 0
	v_mov_b64_e32 v[30:31], 0
	v_mov_b64_e32 v[32:33], 0
	v_mov_b64_e32 v[34:35], 0
	v_mov_b64_e32 v[36:37], 0
	v_mov_b64_e32 v[38:39], 0
	v_mov_b64_e32 v[40:41], 0
	v_mov_b64_e32 v[42:43], 0
	v_mov_b64_e32 v[44:45], 0
	v_mov_b64_e32 v[46:47], 0
	v_mov_b64_e32 v[48:49], 0
	v_mov_b64_e32 v[50:51], 0
	v_mov_b64_e32 v[52:53], 0
	v_mov_b64_e32 v[54:55], 0
	v_mov_b64_e32 v[56:57], 0
	v_mov_b64_e32 v[58:59], 0
	v_mov_b64_e32 v[60:61], 0
	v_mov_b64_e32 v[62:63], 0
	v_mov_b64_e32 v[64:65], 0
	v_mov_b64_e32 v[66:67], 0
	v_mov_b64_e32 v[68:69], 0
	v_mov_b64_e32 v[70:71], 0
	v_mov_b64_e32 v[72:73], 0
	v_mov_b64_e32 v[74:75], 0
	v_mov_b64_e32 v[76:77], 0
	v_mov_b64_e32 v[78:79], 0
	v_mov_b64_e32 v[80:81], 0
	v_mov_b64_e32 v[82:83], 0
	v_mov_b64_e32 v[84:85], 0
	v_mov_b64_e32 v[86:87], 0
	v_mov_b64_e32 v[88:89], 0
	v_mov_b64_e32 v[90:91], 0
	v_mov_b64_e32 v[92:93], 0
	v_mov_b64_e32 v[94:95], 0
	v_mov_b64_e32 v[96:97], 0
	v_mov_b64_e32 v[98:99], 0
	v_mov_b64_e32 v[100:101], 0
	v_mov_b64_e32 v[102:103], 0
	v_mov_b64_e32 v[104:105], 0
	v_mov_b64_e32 v[106:107], 0
	v_mov_b64_e32 v[108:109], 0
	v_mov_b64_e32 v[110:111], 0
	v_mov_b64_e32 v[112:113], 0
	v_mov_b64_e32 v[114:115], 0
	v_mov_b64_e32 v[116:117], 0
	v_mov_b64_e32 v[118:119], 0
	v_mov_b64_e32 v[120:121], 0
	v_mov_b64_e32 v[122:123], 0
	v_mov_b64_e32 v[124:125], 0
	v_mov_b64_e32 v[126:127], 0
	v_cmp_eq_u32_e32 vcc, 1, v220
	s_and_saveexec_b64 s[22:23], vcc
	s_cbranch_execz .LBB0_97
	s_barrier
.LBB0_97:
	s_or_b64 exec, exec, s[22:23]
	v_add_u32_e32 v159, s26, v143
	v_add_u32_e32 v160, 0x2000, v159
	v_readfirstlane_b32 s17, v159
	v_lshl_add_u64 v[208:209], v[208:209], 0, s[0:1]
	s_mov_b32 m0, s17
	v_readfirstlane_b32 s17, v160
	v_add_u32_e32 v161, 0x8000, v153
	s_cmp_eq_u32 s32, 0
	s_cbranch_scc1 .Lp1_w2a
	s_waitcnt vmcnt(18)
	s_branch .Lp1_w2b
.Lp1_w2a:
	s_waitcnt vmcnt(2)
.Lp1_w2b:
	s_barrier
	global_load_lds_dwordx4 v[208:209], off
	v_lshl_add_u64 v[208:209], v[210:211], 0, s[0:1]
	s_mov_b32 m0, s17
	v_readfirstlane_b32 s17, v161
	v_add_u32_e32 v162, 0xa000, v153
	global_load_lds_dwordx4 v[208:209], off
	v_lshl_add_u64 v[208:209], v[212:213], 0, s[0:1]
	s_mov_b32 m0, s17
	v_readfirstlane_b32 s17, v162
	v_add_u32_e32 v163, s27, v143
	global_load_lds_dwordx4 v[208:209], off
	v_lshl_add_u64 v[208:209], v[214:215], 0, s[0:1]
	s_mov_b32 m0, s17
	v_readfirstlane_b32 s17, v163
	v_add_u32_e32 v164, 0x2000, v163
	global_load_lds_dwordx4 v[208:209], off
	v_lshl_add_u64 v[208:209], v[216:217], 0, s[0:1]
	s_mov_b32 m0, s17
	v_readfirstlane_b32 s17, v164
	global_load_lds_dwordx4 v[208:209], off
	v_lshl_add_u64 v[208:209], v[218:219], 0, s[0:1]
	s_mov_b32 m0, s17
	v_and_b32_e32 v221, 15, v128
	global_load_lds_dwordx4 v[208:209], off
	v_bfe_u32 v145, v128, 4, 2
	v_lshlrev_b32_e32 v211, 2, v128
	v_lshlrev_b32_e32 v208, 4, v145
	v_lshlrev_b32_e32 v209, 6, v221
	v_and_b32_e32 v211, 32, v211
	v_bitop3_b32 v209, v208, v211, v209 bitop3:0x36
	v_add_u32_e32 v212, s24, v209
	v_add_u32_e32 v213, s25, v209
	v_add_u32_e32 v214, s26, v209
	v_add_u32_e32 v215, s27, v209
	v_add_u32_e32 v217, 0, v209
	v_lshlrev_b32_e32 v209, 6, v128
	s_movk_i32 s17, 0x3c0
	v_and_or_b32 v208, v209, s17, v208
	v_xad_u32 v211, v208, v211, 0
	v_lshl_add_u64 v[208:209], s[18:19], 0, v[200:201]
	v_lshl_add_u64 v[200:201], s[20:21], 0, v[200:201]
	v_lshl_add_u64 v[200:201], v[200:201], 0, v[202:203]
	v_lshl_add_u64 v[208:209], v[208:209], 0, v[202:203]
	v_lshl_add_u64 v[138:139], s[78:79], 0, v[200:201]
	v_lshl_add_u64 v[200:201], s[20:21], 0, v[204:205]
	v_bfe_u32 v144, v128, 6, 2
	s_cmp_eq_u32 s32, 0
	s_cbranch_scc1 .Lp1_w6a
	s_waitcnt vmcnt(22)
	s_branch .Lp1_w6b
.Lp1_w6a:
	s_waitcnt vmcnt(6)
.Lp1_w6b:
	v_lshlrev_b32_e32 v216, 13, v220
	v_lshl_add_u64 v[134:135], s[82:83], 0, v[208:209]
	v_lshl_add_u64 v[208:209], s[18:19], 0, v[204:205]
	v_lshl_add_u64 v[200:201], v[200:201], 0, v[206:207]
	v_lshlrev_b32_e32 v210, 12, v144
	v_lshl_or_b32 v146, v220, 6, v221
	v_or_b32_e32 v218, 0x800, v216
	v_or_b32_e32 v219, 0x1000, v216
	v_or_b32_e32 v220, 0x1800, v216
	v_lshl_add_u64 v[208:209], v[208:209], 0, v[206:207]
	v_lshl_add_u64 v[140:141], s[78:79], 0, v[200:201]
	v_mov_b32_e32 v0, 0
	v_lshl_add_u64 v[136:137], s[82:83], 0, v[208:209]
	s_mov_b32 s17, -2
	s_mov_b64 s[18:19], 0
	v_add_u32_e32 v166, v212, v210
	v_add_u32_e32 v151, v217, v216
	v_add_u32_e32 v150, v211, v218
	v_add_u32_e32 v149, v211, v219
	v_add_u32_e32 v148, v211, v220
	v_add_u32_e32 v165, v213, v210
	v_add_u32_e32 v156, v214, v210
	v_add_u32_e32 v152, v215, v210
	v_mov_b32_e32 v1, v0
	v_mov_b32_e32 v2, v0
	v_mov_b32_e32 v3, v0
	v_mov_b32_e32 v4, v0
	v_mov_b32_e32 v5, v0
	v_mov_b32_e32 v6, v0
	v_mov_b32_e32 v7, v0
	v_mov_b32_e32 v8, v0
	v_mov_b32_e32 v9, v0
	v_mov_b32_e32 v10, v0
	v_mov_b32_e32 v11, v0
	v_mov_b32_e32 v12, v0
	v_mov_b32_e32 v13, v0
	v_mov_b32_e32 v14, v0
	v_mov_b32_e32 v15, v0
	v_mov_b32_e32 v16, v0
	v_mov_b32_e32 v17, v0
	v_mov_b32_e32 v18, v0
	v_mov_b32_e32 v19, v0
	v_mov_b32_e32 v20, v0
	v_mov_b32_e32 v21, v0
	s_barrier

;     ...
;     __syncthreads();
;   }
.Lp1_exit:
	v_readlane_b32 s34, v255, 0
	v_readlane_b32 s35, v255, 1
	v_readlane_b32 s36, v255, 2
	v_readlane_b32 s37, v255, 3
	v_readlane_b32 s38, v255, 4
	v_readlane_b32 s39, v255, 5
	v_readlane_b32 s40, v255, 6
	v_readlane_b32 s41, v255, 7
	v_readlane_b32 s42, v255, 8
	v_readlane_b32 s43, v255, 9
	v_readlane_b32 s44, v255, 10
	v_readlane_b32 s45, v255, 11
	s_nop 3
